# attention row-sum chains: removed the trailing v_add of 0 (6 sites), on top of v17
# speedup vs baseline: 1.0161x; 1.0161x over previous
.LBB0_77:
	v_mfma_f32_32x32x16_bf16 v[80:95], v[176:179], v[136:139], 0
	v_mfma_f32_32x32x16_bf16 v[64:79], v[168:171], v[136:139], 0
	v_add_u32_e32 v96, s18, v231
	ds_read_b64_tr_b16 v[168:169], v96 offset:24576
	ds_read_b64_tr_b16 v[170:171], v96 offset:25088
	s_waitcnt lgkmcnt(9)
	v_mfma_f32_32x32x16_bf16 v[80:95], v[172:175], v[132:135], v[80:95]
	v_add_f32_e32 v97, v48, v49
	v_add_f32_e32 v97, v50, v97
	v_add_f32_e32 v97, v51, v97
	v_add_f32_e32 v97, v52, v97
	v_add_f32_e32 v97, v53, v97
	v_cvt_pk_bf16_f32 v128, v48, v49
	v_cvt_pk_bf16_f32 v129, v50, v51
	ds_read_b64_tr_b16 v[172:173], v96 offset:28672
	ds_read_b64_tr_b16 v[174:175], v96 offset:29184
	s_waitcnt lgkmcnt(10)
	v_mfma_f32_32x32x16_bf16 v[64:79], v[164:167], v[132:135], v[64:79]
	v_add_f32_e32 v48, v54, v97
	v_add_f32_e32 v48, v55, v48
	v_add_f32_e32 v48, v56, v48
	v_add_f32_e32 v97, v57, v48
	v_cvt_pk_bf16_f32 v130, v52, v53
	v_cvt_pk_bf16_f32 v131, v54, v55
	ds_read_b64_tr_b16 v[48:49], v96 offset:25600
	ds_read_b64_tr_b16 v[50:51], v96 offset:26112
	s_waitcnt lgkmcnt(11)
	v_mfma_f32_32x32x16_bf16 v[80:95], v[160:163], v[124:127], v[80:95]
	v_add_f32_e32 v52, v58, v97
	v_add_f32_e32 v52, v59, v52
	v_add_f32_e32 v52, v60, v52
	v_add_f32_e32 v97, v61, v52
	v_cvt_pk_bf16_f32 v120, v56, v57
	v_cvt_pk_bf16_f32 v121, v58, v59
	ds_read_b64_tr_b16 v[52:53], v96 offset:29696
	ds_read_b64_tr_b16 v[54:55], v96 offset:30208
	s_waitcnt lgkmcnt(12)
	v_mfma_f32_32x32x16_bf16 v[64:79], v[156:159], v[124:127], v[64:79]
	v_add_f32_e32 v56, v62, v97
	v_add_f32_e32 v56, v63, v56
	v_add_f32_e32 v56, v32, v56
	v_add_f32_e32 v97, v33, v56
	v_cvt_pk_bf16_f32 v122, v60, v61
	v_cvt_pk_bf16_f32 v123, v62, v63
	ds_read_b64_tr_b16 v[56:57], v96 offset:26624
	ds_read_b64_tr_b16 v[58:59], v96 offset:27136
	s_waitcnt lgkmcnt(13)
	v_mfma_f32_32x32x16_bf16 v[80:95], v[152:155], v[116:119], v[80:95]
	v_add_f32_e32 v60, v34, v97
	v_add_f32_e32 v60, v35, v60
	v_add_f32_e32 v60, v36, v60
	v_add_f32_e32 v60, v37, v60
	v_cvt_pk_bf16_f32 v112, v32, v33
	v_cvt_pk_bf16_f32 v113, v34, v35
	ds_read_b64_tr_b16 v[32:33], v96 offset:30720
	ds_read_b64_tr_b16 v[34:35], v96 offset:31232
	s_waitcnt lgkmcnt(14)
	v_mfma_f32_32x32x16_bf16 v[64:79], v[148:151], v[116:119], v[64:79]
	v_add_f32_e32 v60, v38, v60
	v_add_f32_e32 v60, v39, v60
	v_add_f32_e32 v60, v40, v60
	v_add_f32_e32 v60, v41, v60
	v_cvt_pk_bf16_f32 v114, v36, v37
	v_cvt_pk_bf16_f32 v115, v38, v39
	ds_read_b64_tr_b16 v[36:37], v96 offset:27648
	ds_read_b64_tr_b16 v[38:39], v96 offset:28160
	s_waitcnt lgkmcnt(14)
	v_mfma_f32_32x32x16_bf16 v[80:95], v[144:147], v[108:111], v[80:95]
	v_add_f32_e32 v60, v42, v60
	v_add_f32_e32 v60, v43, v60
	v_add_f32_e32 v60, v44, v60
	v_add_f32_e32 v60, v45, v60
	v_cvt_pk_bf16_f32 v104, v40, v41
	v_cvt_pk_bf16_f32 v105, v42, v43
	ds_read_b64_tr_b16 v[40:41], v96 offset:31744
	ds_read_b64_tr_b16 v[42:43], v96 offset:32256
	v_mfma_f32_32x32x16_bf16 v[64:79], v[140:143], v[108:111], v[64:79]
	v_add_f32_e32 v60, v46, v60
	v_add_f32_e32 v60, v47, v60
	v_cvt_pk_bf16_f32 v106, v44, v45
	v_cvt_pk_bf16_f32 v107, v46, v47
	v_lshl_add_u64 v[176:177], v[186:187], 0, s[12:13]
	v_lshl_add_u64 v[44:45], v[176:177], 0, s[70:71]
	v_lshl_add_u64 v[178:179], v[184:185], 0, s[12:13]
	s_add_i32 s18, s50, s42
	s_mov_b32 s19, m0
	s_mov_b32 m0, s18
	s_nop 0
	global_load_lds_dwordx4 v[44:45], off
	s_mov_b32 m0, s19
	v_lshl_add_u64 v[44:45], v[178:179], 0, s[78:79]
	s_add_i32 s18, s48, s43
	s_mov_b32 s19, m0
	s_mov_b32 m0, s18
	s_nop 0
	global_load_lds_dwordx4 v[44:45], off
	s_mov_b32 m0, s19
	v_max_f32_e32 v44, v80, v81
	v_max3_f32 v45, v82, v83, v65
	v_max3_f32 v44, v44, v64, v66
	v_max3_f32 v44, v44, v67, v84
	v_max3_f32 v45, v45, v86, v87
	v_max3_f32 v44, v44, v85, v68
	v_max3_f32 v45, v45, v70, v71
	v_max3_f32 v44, v44, v69, v88
	v_max3_f32 v45, v45, v90, v91
	v_max3_f32 v44, v44, v89, v72
	v_max3_f32 v45, v45, v74, v75
	v_max3_f32 v44, v44, v73, v92
	v_max3_f32 v45, v45, v94, v95
	v_max3_f32 v44, v44, v93, v76
	v_max3_f32 v45, v45, v78, v79
	v_max3_f32 v44, v44, v77, v45
	v_mov_b32_e32 v45, v44
	s_nop 1
	v_permlane32_swap_b32_e32 v44, v45
	v_max_f32_e32 v44, v44, v45
	v_cmp_lt_f32_e32 vcc, s58, v44
	s_cmp_lg_u64 vcc, 0
	v_add_f32_e32 v183, v234, v60
	s_cselect_b64 s[18:19], -1, 0
	s_cbranch_vccnz .LBB0_85

.LBB0_80:
	s_add_i32 s18, s48, 0x2000
	s_cmpk_lg_i32 s48, 0x4000
	s_cselect_b32 s45, s18, 0
	v_mfma_f32_32x32x16_bf16 v[48:63], v[60:63], v[136:139], 0
	v_mfma_f32_32x32x16_bf16 v[32:47], v[44:47], v[136:139], 0
	v_add_u32_e32 v96, s50, v231
	ds_read_b64_tr_b16 v[140:141], v96 offset:24576
	ds_read_b64_tr_b16 v[142:143], v96 offset:25088
	s_waitcnt lgkmcnt(9)
	v_mfma_f32_32x32x16_bf16 v[48:63], v[144:147], v[132:135], v[48:63]
	v_add_f32_e32 v97, v80, v81
	v_add_f32_e32 v97, v82, v97
	v_add_f32_e32 v97, v83, v97
	v_add_f32_e32 v97, v84, v97
	v_add_f32_e32 v97, v85, v97
	v_cvt_pk_bf16_f32 v128, v80, v81
	v_cvt_pk_bf16_f32 v129, v82, v83
	ds_read_b64_tr_b16 v[144:145], v96 offset:28672
	ds_read_b64_tr_b16 v[146:147], v96 offset:29184
	s_waitcnt lgkmcnt(10)
	v_mfma_f32_32x32x16_bf16 v[32:47], v[172:175], v[132:135], v[32:47]
	v_add_f32_e32 v80, v86, v97
	v_add_f32_e32 v80, v87, v80
	v_add_f32_e32 v80, v88, v80
	v_add_f32_e32 v97, v89, v80
	v_cvt_pk_bf16_f32 v130, v84, v85
	v_cvt_pk_bf16_f32 v131, v86, v87
	ds_read_b64_tr_b16 v[80:81], v96 offset:25600
	ds_read_b64_tr_b16 v[82:83], v96 offset:26112
	s_waitcnt lgkmcnt(11)
	v_mfma_f32_32x32x16_bf16 v[48:63], v[168:171], v[124:127], v[48:63]
	v_add_f32_e32 v84, v90, v97
	v_add_f32_e32 v84, v91, v84
	v_add_f32_e32 v84, v92, v84
	v_add_f32_e32 v97, v93, v84
	v_cvt_pk_bf16_f32 v120, v88, v89
	v_cvt_pk_bf16_f32 v121, v90, v91
	ds_read_b64_tr_b16 v[84:85], v96 offset:29696
	ds_read_b64_tr_b16 v[86:87], v96 offset:30208
	s_waitcnt lgkmcnt(12)
	v_mfma_f32_32x32x16_bf16 v[32:47], v[164:167], v[124:127], v[32:47]
	v_add_f32_e32 v88, v94, v97
	v_add_f32_e32 v88, v95, v88
	v_add_f32_e32 v88, v64, v88
	v_add_f32_e32 v97, v65, v88
	v_cvt_pk_bf16_f32 v122, v92, v93
	v_cvt_pk_bf16_f32 v123, v94, v95
	ds_read_b64_tr_b16 v[88:89], v96 offset:26624
	ds_read_b64_tr_b16 v[90:91], v96 offset:27136
	s_waitcnt lgkmcnt(13)
	v_mfma_f32_32x32x16_bf16 v[48:63], v[160:163], v[116:119], v[48:63]
	v_add_f32_e32 v92, v66, v97
	v_add_f32_e32 v92, v67, v92
	v_add_f32_e32 v92, v68, v92
	v_add_f32_e32 v92, v69, v92
	v_cvt_pk_bf16_f32 v112, v64, v65
	v_cvt_pk_bf16_f32 v113, v66, v67
	ds_read_b64_tr_b16 v[64:65], v96 offset:30720
	ds_read_b64_tr_b16 v[66:67], v96 offset:31232
	s_waitcnt lgkmcnt(14)
	v_mfma_f32_32x32x16_bf16 v[32:47], v[156:159], v[116:119], v[32:47]
	v_add_f32_e32 v92, v70, v92
	v_add_f32_e32 v92, v71, v92
	v_add_f32_e32 v92, v72, v92
	v_add_f32_e32 v92, v73, v92
	v_cvt_pk_bf16_f32 v114, v68, v69
	v_cvt_pk_bf16_f32 v115, v70, v71
	ds_read_b64_tr_b16 v[68:69], v96 offset:27648
	ds_read_b64_tr_b16 v[70:71], v96 offset:28160
	s_waitcnt lgkmcnt(14)
	v_mfma_f32_32x32x16_bf16 v[48:63], v[152:155], v[108:111], v[48:63]
	v_add_f32_e32 v92, v74, v92
	v_add_f32_e32 v92, v75, v92
	v_add_f32_e32 v92, v76, v92
	v_add_f32_e32 v92, v77, v92
	v_cvt_pk_bf16_f32 v104, v72, v73
	v_cvt_pk_bf16_f32 v105, v74, v75
	ds_read_b64_tr_b16 v[72:73], v96 offset:31744
	ds_read_b64_tr_b16 v[74:75], v96 offset:32256
	v_mfma_f32_32x32x16_bf16 v[32:47], v[148:151], v[108:111], v[32:47]
	v_add_f32_e32 v92, v78, v92
	v_add_f32_e32 v92, v79, v92
	v_cvt_pk_bf16_f32 v106, v76, v77
	v_cvt_pk_bf16_f32 v107, v78, v79
	s_mov_b64 s[18:19], 0xd620000
	v_lshl_add_u64 v[76:77], v[176:177], 0, s[18:19]
	s_add_i32 s18, s48, s42
	s_mov_b32 s19, m0
	s_mov_b32 m0, s18
	s_nop 0
	global_load_lds_dwordx4 v[76:77], off
	s_mov_b32 m0, s19
	s_mov_b64 s[18:19], 0x117e0000
	v_lshl_add_u64 v[76:77], v[178:179], 0, s[18:19]
	s_add_i32 s18, s45, s43
	s_mov_b32 s19, m0
	s_mov_b32 m0, s18
	s_nop 0
	global_load_lds_dwordx4 v[76:77], off
	s_mov_b32 m0, s19
	v_max_f32_e32 v76, v48, v49
	v_max3_f32 v77, v50, v51, v33
	v_max3_f32 v76, v76, v32, v34
	v_max3_f32 v76, v76, v35, v52
	v_max3_f32 v77, v77, v54, v55
	v_max3_f32 v76, v76, v53, v36
	v_max3_f32 v77, v77, v38, v39
	v_max3_f32 v76, v76, v37, v56
	v_max3_f32 v77, v77, v58, v59
	v_max3_f32 v76, v76, v57, v40
	v_max3_f32 v77, v77, v42, v43
	v_max3_f32 v76, v76, v41, v60
	v_max3_f32 v77, v77, v62, v63
	v_max3_f32 v76, v76, v61, v44
	v_max3_f32 v77, v77, v46, v47
	v_max3_f32 v76, v76, v45, v77
	v_mov_b32_e32 v77, v76
	s_nop 1
	v_permlane32_swap_b32_e32 v76, v77
	v_max_f32_e32 v76, v76, v77
	v_cmp_lt_f32_e32 vcc, s58, v76
	s_cmp_lg_u64 vcc, 0
	v_add_f32_e32 v234, v183, v92
	s_cselect_b64 s[18:19], -1, 0
	s_cbranch_vccnz .LBB0_88

.LBB0_97:
	v_mfma_f32_32x32x16_bf16 v[80:95], v[176:179], v[136:139], 0
	v_mfma_f32_32x32x16_bf16 v[64:79], v[168:171], v[136:139], 0
	v_add_u32_e32 v96, s48, v231
	ds_read_b64_tr_b16 v[168:169], v96 offset:24576
	ds_read_b64_tr_b16 v[170:171], v96 offset:25088
	s_waitcnt lgkmcnt(3)
	v_mfma_f32_32x32x16_bf16 v[80:95], v[172:175], v[132:135], v[80:95]
	v_add_f32_e32 v97, v48, v49
	v_add_f32_e32 v97, v50, v97
	v_add_f32_e32 v97, v51, v97
	v_add_f32_e32 v97, v52, v97
	v_add_f32_e32 v97, v53, v97
	v_cvt_pk_bf16_f32 v128, v48, v49
	v_cvt_pk_bf16_f32 v129, v50, v51
	ds_read_b64_tr_b16 v[172:173], v96 offset:28672
	ds_read_b64_tr_b16 v[174:175], v96 offset:29184
	s_waitcnt lgkmcnt(4)
	v_mfma_f32_32x32x16_bf16 v[64:79], v[164:167], v[132:135], v[64:79]
	v_add_f32_e32 v48, v54, v97
	v_add_f32_e32 v48, v55, v48
	v_add_f32_e32 v48, v56, v48
	v_add_f32_e32 v97, v57, v48
	v_cvt_pk_bf16_f32 v130, v52, v53
	v_cvt_pk_bf16_f32 v131, v54, v55
	ds_read_b64_tr_b16 v[48:49], v96 offset:25600
	ds_read_b64_tr_b16 v[50:51], v96 offset:26112
	s_waitcnt lgkmcnt(11)
	v_mfma_f32_32x32x16_bf16 v[80:95], v[160:163], v[124:127], v[80:95]
	v_add_f32_e32 v52, v58, v97
	v_add_f32_e32 v52, v59, v52
	v_add_f32_e32 v52, v60, v52
	v_add_f32_e32 v97, v61, v52
	v_cvt_pk_bf16_f32 v120, v56, v57
	v_cvt_pk_bf16_f32 v121, v58, v59
	ds_read_b64_tr_b16 v[52:53], v96 offset:29696
	ds_read_b64_tr_b16 v[54:55], v96 offset:30208
	s_waitcnt lgkmcnt(12)
	v_mfma_f32_32x32x16_bf16 v[64:79], v[156:159], v[124:127], v[64:79]
	v_add_f32_e32 v56, v62, v97
	v_add_f32_e32 v56, v63, v56
	v_add_f32_e32 v56, v32, v56
	v_add_f32_e32 v97, v33, v56
	v_cvt_pk_bf16_f32 v122, v60, v61
	v_cvt_pk_bf16_f32 v123, v62, v63
	ds_read_b64_tr_b16 v[56:57], v96 offset:26624
	ds_read_b64_tr_b16 v[58:59], v96 offset:27136
	s_waitcnt lgkmcnt(13)
	v_mfma_f32_32x32x16_bf16 v[80:95], v[152:155], v[116:119], v[80:95]
	v_add_f32_e32 v60, v34, v97
	v_add_f32_e32 v60, v35, v60
	v_add_f32_e32 v60, v36, v60
	v_add_f32_e32 v60, v37, v60
	v_cvt_pk_bf16_f32 v112, v32, v33
	v_cvt_pk_bf16_f32 v113, v34, v35
	ds_read_b64_tr_b16 v[32:33], v96 offset:30720
	ds_read_b64_tr_b16 v[34:35], v96 offset:31232
	s_waitcnt lgkmcnt(14)
	v_mfma_f32_32x32x16_bf16 v[64:79], v[148:151], v[116:119], v[64:79]
	v_add_f32_e32 v60, v38, v60
	v_add_f32_e32 v60, v39, v60
	v_add_f32_e32 v60, v40, v60
	v_add_f32_e32 v60, v41, v60
	v_cvt_pk_bf16_f32 v114, v36, v37
	v_cvt_pk_bf16_f32 v115, v38, v39
	ds_read_b64_tr_b16 v[36:37], v96 offset:27648
	ds_read_b64_tr_b16 v[38:39], v96 offset:28160
	s_waitcnt lgkmcnt(14)
	v_mfma_f32_32x32x16_bf16 v[80:95], v[144:147], v[108:111], v[80:95]
	v_add_f32_e32 v60, v42, v60
	v_add_f32_e32 v60, v43, v60
	v_add_f32_e32 v60, v44, v60
	v_add_f32_e32 v60, v45, v60
	v_cvt_pk_bf16_f32 v104, v40, v41
	v_cvt_pk_bf16_f32 v105, v42, v43
	ds_read_b64_tr_b16 v[40:41], v96 offset:31744
	ds_read_b64_tr_b16 v[42:43], v96 offset:32256
	v_mfma_f32_32x32x16_bf16 v[64:79], v[140:143], v[108:111], v[64:79]
	v_add_f32_e32 v60, v46, v60
	v_add_f32_e32 v60, v47, v60
	v_cvt_pk_bf16_f32 v106, v44, v45
	v_cvt_pk_bf16_f32 v107, v46, v47
	s_add_i32 s4, s18, 1
	s_cmp_ge_i32 s4, s44
	s_cselect_b64 s[14:15], -1, 0
	s_and_b64 vcc, exec, s[14:15]
	v_lshl_add_u64 v[204:205], v[200:201], 0, s[12:13]
	s_cbranch_vccnz .LBB0_99
	s_mov_b64 s[4:5], 0xd5e0000
	s_add_i32 s16, s45, s42
	v_lshl_add_u64 v[44:45], v[204:205], 0, s[4:5]
	s_mov_b32 s4, m0
	s_mov_b32 m0, s16
	s_nop 0
	global_load_lds_dwordx4 v[44:45], off
	s_mov_b32 m0, s4

.LBB0_106:
	v_mfma_f32_32x32x16_bf16 v[48:63], v[176:179], v[136:139], 0
	v_mfma_f32_32x32x16_bf16 v[32:47], v[168:171], v[136:139], 0
	v_add_u32_e32 v96, s45, v231
	ds_read_b64_tr_b16 v[188:189], v96 offset:24576
	ds_read_b64_tr_b16 v[190:191], v96 offset:25088
	s_waitcnt lgkmcnt(9)
	v_mfma_f32_32x32x16_bf16 v[48:63], v[172:175], v[132:135], v[48:63]
	v_add_f32_e32 v97, v80, v81
	v_add_f32_e32 v97, v82, v97
	v_add_f32_e32 v97, v83, v97
	v_add_f32_e32 v97, v84, v97
	v_add_f32_e32 v97, v85, v97
	v_cvt_pk_bf16_f32 v128, v80, v81
	v_cvt_pk_bf16_f32 v129, v82, v83
	ds_read_b64_tr_b16 v[184:185], v96 offset:28672
	ds_read_b64_tr_b16 v[186:187], v96 offset:29184
	s_waitcnt lgkmcnt(10)
	v_mfma_f32_32x32x16_bf16 v[32:47], v[164:167], v[132:135], v[32:47]
	v_add_f32_e32 v80, v86, v97
	v_add_f32_e32 v80, v87, v80
	v_add_f32_e32 v80, v88, v80
	v_add_f32_e32 v80, v89, v80
	v_cvt_pk_bf16_f32 v130, v84, v85
	v_cvt_pk_bf16_f32 v131, v86, v87
	ds_read_b64_tr_b16 v[180:181], v96 offset:25600
	ds_read_b64_tr_b16 v[182:183], v96 offset:26112
	s_waitcnt lgkmcnt(11)
	v_mfma_f32_32x32x16_bf16 v[48:63], v[160:163], v[124:127], v[48:63]
	v_add_f32_e32 v80, v90, v80
	v_add_f32_e32 v80, v91, v80
	v_add_f32_e32 v80, v92, v80
	v_add_f32_e32 v80, v93, v80
	v_cvt_pk_bf16_f32 v120, v88, v89
	v_cvt_pk_bf16_f32 v121, v90, v91
	ds_read_b64_tr_b16 v[88:89], v96 offset:29696
	ds_read_b64_tr_b16 v[90:91], v96 offset:30208
	s_waitcnt lgkmcnt(12)
	v_mfma_f32_32x32x16_bf16 v[32:47], v[156:159], v[124:127], v[32:47]
	v_add_f32_e32 v80, v94, v80
	v_add_f32_e32 v80, v95, v80
	v_add_f32_e32 v80, v64, v80
	v_add_f32_e32 v80, v65, v80
	v_cvt_pk_bf16_f32 v122, v92, v93
	v_cvt_pk_bf16_f32 v123, v94, v95
	ds_read_b64_tr_b16 v[84:85], v96 offset:26624
	ds_read_b64_tr_b16 v[86:87], v96 offset:27136
	s_waitcnt lgkmcnt(13)
	v_mfma_f32_32x32x16_bf16 v[48:63], v[152:155], v[116:119], v[48:63]
	v_add_f32_e32 v80, v66, v80
	v_add_f32_e32 v80, v67, v80
	v_add_f32_e32 v80, v68, v80
	v_add_f32_e32 v92, v69, v80
	v_cvt_pk_bf16_f32 v112, v64, v65
	v_cvt_pk_bf16_f32 v113, v66, v67
	ds_read_b64_tr_b16 v[80:81], v96 offset:30720
	ds_read_b64_tr_b16 v[82:83], v96 offset:31232
	s_waitcnt lgkmcnt(14)
	v_mfma_f32_32x32x16_bf16 v[32:47], v[148:151], v[116:119], v[32:47]
	v_add_f32_e32 v64, v70, v92
	v_add_f32_e32 v64, v71, v64
	v_add_f32_e32 v64, v72, v64
	v_add_f32_e32 v64, v73, v64
	v_cvt_pk_bf16_f32 v114, v68, v69
	v_cvt_pk_bf16_f32 v115, v70, v71
	ds_read_b64_tr_b16 v[68:69], v96 offset:27648
	ds_read_b64_tr_b16 v[70:71], v96 offset:28160
	s_waitcnt lgkmcnt(14)
	v_mfma_f32_32x32x16_bf16 v[48:63], v[144:147], v[108:111], v[48:63]
	v_add_f32_e32 v64, v74, v64
	v_add_f32_e32 v64, v75, v64
	v_add_f32_e32 v64, v76, v64
	v_add_f32_e32 v92, v77, v64
	v_cvt_pk_bf16_f32 v104, v72, v73
	v_cvt_pk_bf16_f32 v105, v74, v75
	ds_read_b64_tr_b16 v[64:65], v96 offset:31744
	ds_read_b64_tr_b16 v[66:67], v96 offset:32256
	v_mfma_f32_32x32x16_bf16 v[32:47], v[140:143], v[108:111], v[32:47]
	v_add_f32_e32 v72, v78, v92
	v_add_f32_e32 v72, v79, v72
	v_cvt_pk_bf16_f32 v106, v76, v77
	v_cvt_pk_bf16_f32 v107, v78, v79
	s_add_i32 s46, s18, 2
	s_cmp_ge_i32 s46, s44
	s_cselect_b64 s[16:17], -1, 0
	s_and_b64 vcc, exec, s[16:17]
	s_cbranch_vccnz .LBB0_108
	s_add_i32 s4, s47, s42
	v_lshl_add_u64 v[74:75], v[204:205], 0, s[70:71]
	s_mov_b32 s5, m0
	s_mov_b32 m0, s4
	s_nop 0
	global_load_lds_dwordx4 v[74:75], off
	s_mov_b32 m0, s5

.LBB0_163:
	s_ashr_i32 s25, s24, 31
	s_lshl_b64 s[26:27], s[24:25], 15
	v_add_f32_e32 v8, v8, v12
	v_add_f32_e32 v17, v31, v17
	v_add_f32_e32 v18, v18, v15
	v_add_f32_e32 v31, 0, v14
	v_add_f32_e32 v9, v9, v16
	v_lshl_add_u64 v[14:15], v[0:1], 0, s[26:27]
	v_mul_f32_e32 v8, 0xbfb8aa3b, v8
	global_store_dword v[14:15], v8, off
	v_add_f32_e32 v8, v9, v12
	v_add_f32_e32 v11, v33, v11
	v_add_f32_e32 v33, 0, v10
	v_add_f32_e32 v10, v19, v24
	v_mul_f32_e32 v8, 0xbfb8aa3b, v8
	global_store_dword v[14:15], v8, off offset:256
	v_add_f32_e32 v8, v10, v12
	s_add_i32 s25, s31, 0
	v_mul_f32_e32 v16, 0xbfb8aa3b, v8
	v_mov_b32_e32 v8, s25
	ds_read_b96 v[8:10], v8
	v_add_f32_e32 v21, v23, v21
	v_add_f32_e32 v23, v25, v26
	global_store_dword v[14:15], v16, off offset:512
	s_waitcnt lgkmcnt(0)
	v_add_f32_e32 v8, v12, v8
	v_add_f32_e32 v16, v23, v12
	v_add_f32_e32 v12, v20, v8
	v_mul_f32_e32 v12, 0xbfb8aa3b, v12
	global_store_dword v[14:15], v12, off offset:1024
	v_add_f32_e32 v12, v21, v8
	v_add_f32_e32 v22, v28, v22
	v_mul_f32_e32 v12, 0xbfb8aa3b, v12
	global_store_dword v[14:15], v12, off offset:1280
	v_add_f32_e32 v12, v22, v8
	v_add_f32_e32 v27, v29, v27
	v_mul_f32_e32 v12, 0xbfb8aa3b, v12
	global_store_dword v[14:15], v12, off offset:1536
	v_add_f32_e32 v12, v27, v8
	v_add_f32_e32 v8, v8, v9
	v_add_f32_e32 v9, v31, v8
	v_mul_f32_e32 v9, 0xbfb8aa3b, v9
	global_store_dword v[14:15], v9, off offset:2048
	v_add_f32_e32 v9, v18, v8
	v_mul_f32_e32 v9, 0xbfb8aa3b, v9
	global_store_dword v[14:15], v9, off offset:2304
	v_add_f32_e32 v9, v17, v8
	v_add_f32_e32 v30, v32, v30
	v_mul_f32_e32 v9, 0xbfb8aa3b, v9
	global_store_dword v[14:15], v9, off offset:2560
	v_add_f32_e32 v9, v30, v8
	v_mul_f32_e32 v9, 0xbfb8aa3b, v9
	v_add_f32_e32 v8, v8, v10
	global_store_dword v[14:15], v9, off offset:2816
	v_add_f32_e32 v9, v33, v8
	v_mul_f32_e32 v9, 0xbfb8aa3b, v9
	global_store_dword v[14:15], v9, off offset:3072
	v_add_f32_e32 v9, v11, v8
	v_add_f32_e32 v34, v36, v34
	v_add_f32_e32 v13, v35, v13
	v_mul_f32_e32 v9, 0xbfb8aa3b, v9
	global_store_dword v[14:15], v9, off offset:3328
	v_add_f32_e32 v9, v13, v8
	v_add_f32_e32 v8, v34, v8
	s_add_i32 s24, s24, s72
	v_mul_f32_e32 v16, 0xbfb8aa3b, v16
	v_mul_f32_e32 v12, 0xbfb8aa3b, v12
	v_mul_f32_e32 v9, 0xbfb8aa3b, v9
	v_mul_f32_e32 v8, 0xbfb8aa3b, v8
	s_cmp_gt_i32 s24, 63
	global_store_dword v[14:15], v16, off offset:768
	global_store_dword v[14:15], v12, off offset:1792
	global_store_dword v[14:15], v9, off offset:3584
	global_store_dword v[14:15], v8, off offset:3840
	s_barrier
	s_cbranch_scc1 .LBB0_175
